# v15 + pass2 steps (2)+(3): one wait per k-step (all eight operand reads a k-step ahead) instead of four
# speedup vs baseline: 1.0039x; 1.0026x over previous
.LBB0_1334:
	s_mul_i32 s22, s22, 0xe400
	s_add_i32 s27, s22, 0
	v_add3_u32 v147, s27, v104, v109
	s_add_i32 s29, s27, s19
	ds_read_b64 v[148:149], v147
	ds_read_b64 v[150:151], v147 offset:32
	ds_read_b64 v[152:153], v147 offset:4352
	ds_read_b64 v[154:155], v147 offset:4384
	ds_read_b64 v[196:197], v147 offset:8704
	ds_read_b64 v[198:199], v147 offset:8736
	ds_read_b64 v[200:201], v147 offset:13056
	ds_read_b64 v[202:203], v147 offset:13088
	v_cvt_pk_bf16_f32 v126, v26, v27
	v_cvt_pk_bf16_f32 v127, v28, v29
	v_cvt_pk_bf16_f32 v128, v30, v31
	v_cvt_pk_bf16_f32 v129, v32, v33
	ds_read_b64 v[156:157], v147 offset:64
	ds_read_b64 v[158:159], v147 offset:96
	ds_read_b64 v[160:161], v147 offset:4416
	ds_read_b64 v[162:163], v147 offset:4448
	ds_read_b64 v[204:205], v147 offset:8768
	ds_read_b64 v[206:207], v147 offset:8800
	ds_read_b64 v[208:209], v147 offset:13120
	ds_read_b64 v[210:211], v147 offset:13152
	v_cvt_pk_bf16_f32 v130, v34, v35
	v_cvt_pk_bf16_f32 v131, v36, v37
	v_cvt_pk_bf16_f32 v132, v38, v39
	v_cvt_pk_bf16_f32 v133, v40, v41
	s_waitcnt lgkmcnt(8)
	v_mfma_f32_16x16x32_bf16 v[62:65], v[126:129], v[148:151], 0
	v_mfma_f32_16x16x32_bf16 v[58:61], v[126:129], v[152:155], 0
	v_mfma_f32_16x16x32_bf16 v[164:167], v[196:199], v[148:151], 0
	v_mfma_f32_16x16x32_bf16 v[168:171], v[196:199], v[152:155], 0
	v_mfma_f32_16x16x32_bf16 v[172:175], v[200:203], v[152:155], 0
	ds_read_b64 v[148:149], v147 offset:128
	ds_read_b64 v[150:151], v147 offset:160
	ds_read_b64 v[152:153], v147 offset:4480
	ds_read_b64 v[154:155], v147 offset:4512
	ds_read_b64 v[196:197], v147 offset:8832
	ds_read_b64 v[198:199], v147 offset:8864
	ds_read_b64 v[200:201], v147 offset:13184
	ds_read_b64 v[202:203], v147 offset:13216
	v_cvt_pk_bf16_f32 v134, v42, v43
	v_cvt_pk_bf16_f32 v135, v44, v45
	v_cvt_pk_bf16_f32 v136, v46, v47
	v_cvt_pk_bf16_f32 v137, v48, v49
	s_waitcnt lgkmcnt(8)
	v_mfma_f32_16x16x32_bf16 v[62:65], v[130:133], v[156:159], v[62:65]
	v_mfma_f32_16x16x32_bf16 v[58:61], v[130:133], v[160:163], v[58:61]
	v_mfma_f32_16x16x32_bf16 v[164:167], v[204:207], v[156:159], v[164:167]
	v_mfma_f32_16x16x32_bf16 v[168:171], v[204:207], v[160:163], v[168:171]
	v_mfma_f32_16x16x32_bf16 v[172:175], v[208:211], v[160:163], v[172:175]
	ds_read_b64 v[156:157], v147 offset:192
	ds_read_b64 v[158:159], v147 offset:224
	ds_read_b64 v[160:161], v147 offset:4544
	ds_read_b64 v[162:163], v147 offset:4576
	ds_read_b64 v[204:205], v147 offset:8896
	ds_read_b64 v[206:207], v147 offset:8928
	ds_read_b64 v[208:209], v147 offset:13248
	ds_read_b64 v[210:211], v147 offset:13280
	v_cvt_pk_bf16_f32 v138, v50, v51
	v_cvt_pk_bf16_f32 v139, v52, v53
	v_cvt_pk_bf16_f32 v140, v54, v55
	v_cvt_pk_bf16_f32 v141, v56, v57
	s_waitcnt lgkmcnt(8)
	v_mfma_f32_16x16x32_bf16 v[62:65], v[134:137], v[148:151], v[62:65]
	v_mfma_f32_16x16x32_bf16 v[58:61], v[134:137], v[152:155], v[58:61]
	v_mfma_f32_16x16x32_bf16 v[164:167], v[196:199], v[148:151], v[164:167]
	v_mfma_f32_16x16x32_bf16 v[168:171], v[196:199], v[152:155], v[168:171]
	v_mfma_f32_16x16x32_bf16 v[172:175], v[200:203], v[152:155], v[172:175]
	v_add_u32_e32 v176, s27, v106
	v_add_u32_e32 v68, v176, v123
	ds_read_b64_tr_b16 v[66:67], v68 offset:37888
	ds_read_b64_tr_b16 v[68:69], v68 offset:43008
	s_waitcnt lgkmcnt(2)
	v_mfma_f32_16x16x32_bf16 v[62:65], v[138:141], v[156:159], v[62:65]
	v_mfma_f32_16x16x32_bf16 v[58:61], v[138:141], v[160:163], v[58:61]
	v_mfma_f32_16x16x32_bf16 v[164:167], v[204:207], v[156:159], v[164:167]
	v_mfma_f32_16x16x32_bf16 v[168:171], v[204:207], v[160:163], v[168:171]
	v_mfma_f32_16x16x32_bf16 v[172:175], v[208:211], v[160:163], v[172:175]
	v_add_u32_e32 v125, s27, v105
	v_add_u32_e32 v134, v176, v110
	v_mov_b32_e32 v177, s55
	v_mov_b32_e32 v72, v16
	v_mov_b32_e32 v73, v16
	s_nop 0
	v_cndmask_b32_e64 v165, 0, v165, s[6:7]
	v_cndmask_b32_e64 v166, v166, 0, s[8:9]
	v_cndmask_b32_e64 v167, v167, 0, s[10:11]
	v_cndmask_b32_e64 v164, v164, v177, s[4:5]
	v_cvt_pk_bf16_f32 v70, v164, v165
	v_cvt_pk_bf16_f32 v71, v166, v167
	v_cndmask_b32_e64 v172, v172, v177, s[4:5]
	v_cndmask_b32_e64 v173, v173, 0, s[12:13]
	v_cndmask_b32_e64 v174, v174, 0, s[14:15]
	v_cndmask_b32_e64 v175, v175, 0, s[16:17]
	s_waitcnt lgkmcnt(0)
	v_mfma_f32_16x16x32_bf16 v[62:65], v[66:69], v[70:73], v[62:65]
	v_cvt_pk_bf16_f32 v70, v168, v169
	v_cvt_pk_bf16_f32 v71, v170, v171
	v_cvt_pk_bf16_f32 v72, v172, v173
	v_cvt_pk_bf16_f32 v73, v174, v175
	s_nop 1
	v_mfma_f32_16x16x32_bf16 v[58:61], v[66:69], v[70:73], v[58:61]
	ds_read_b128 v[160:163], v125 offset:56832
	ds_read_b64_tr_b16 v[148:149], v134 offset:27648
	ds_read_b64_tr_b16 v[150:151], v134 offset:32768
	ds_read_b128 v[164:167], v125 offset:56896
	ds_read_b64_tr_b16 v[152:153], v134 offset:27680
	ds_read_b64_tr_b16 v[154:155], v134 offset:32800
	s_waitcnt lgkmcnt(3)
	v_pk_mul_f32 v[26:27], v[26:27], v[160:161]
	v_pk_mul_f32 v[28:29], v[28:29], v[162:163]
	ds_read_b128 v[168:171], v125 offset:56960
	ds_read_b64_tr_b16 v[156:157], v134 offset:27712
	ds_read_b64_tr_b16 v[158:159], v134 offset:32832
	v_mfma_f32_16x16x32_bf16 v[26:29], v[148:151], v[66:69], v[26:29]
	s_waitcnt lgkmcnt(3)
	v_pk_mul_f32 v[30:31], v[30:31], v[164:165]
	v_pk_mul_f32 v[32:33], v[32:33], v[166:167]
	ds_read_b128 v[160:163], v125 offset:57024
	ds_read_b64_tr_b16 v[148:149], v134 offset:27744
	ds_read_b64_tr_b16 v[150:151], v134 offset:32864
	v_mfma_f32_16x16x32_bf16 v[30:33], v[152:155], v[66:69], v[30:33]
	s_waitcnt lgkmcnt(3)
	v_pk_mul_f32 v[34:35], v[34:35], v[168:169]
	v_pk_mul_f32 v[36:37], v[36:37], v[170:171]
	ds_read_b128 v[164:167], v125 offset:57088
	ds_read_b64_tr_b16 v[152:153], v134 offset:27776
	ds_read_b64_tr_b16 v[154:155], v134 offset:32896
	v_mfma_f32_16x16x32_bf16 v[34:37], v[156:159], v[66:69], v[34:37]
	s_waitcnt lgkmcnt(3)
	v_pk_mul_f32 v[38:39], v[38:39], v[160:161]
	v_pk_mul_f32 v[40:41], v[40:41], v[162:163]
	ds_read_b128 v[168:171], v125 offset:57152
	ds_read_b64_tr_b16 v[156:157], v134 offset:27808
	ds_read_b64_tr_b16 v[158:159], v134 offset:32928
	v_mfma_f32_16x16x32_bf16 v[38:41], v[148:151], v[66:69], v[38:41]
	s_waitcnt lgkmcnt(3)
	v_pk_mul_f32 v[42:43], v[42:43], v[164:165]
	v_pk_mul_f32 v[44:45], v[44:45], v[166:167]
	ds_read_b128 v[160:163], v125 offset:57216
	ds_read_b64_tr_b16 v[148:149], v134 offset:27840
	ds_read_b64_tr_b16 v[150:151], v134 offset:32960
	v_mfma_f32_16x16x32_bf16 v[42:45], v[152:155], v[66:69], v[42:45]
	s_waitcnt lgkmcnt(3)
	v_pk_mul_f32 v[46:47], v[46:47], v[168:169]
	v_pk_mul_f32 v[48:49], v[48:49], v[170:171]
	ds_read_b128 v[164:167], v125 offset:57280
	ds_read_b64_tr_b16 v[152:153], v134 offset:27872
	ds_read_b64_tr_b16 v[154:155], v134 offset:32992
	v_mfma_f32_16x16x32_bf16 v[46:49], v[156:159], v[66:69], v[46:49]
	s_waitcnt lgkmcnt(3)
	v_pk_mul_f32 v[50:51], v[50:51], v[160:161]
	v_pk_mul_f32 v[52:53], v[52:53], v[162:163]
	s_nop 1
	v_mfma_f32_16x16x32_bf16 v[50:53], v[148:151], v[66:69], v[50:53]
	s_waitcnt lgkmcnt(0)
	v_pk_mul_f32 v[54:55], v[54:55], v[164:165]
	v_pk_mul_f32 v[56:57], v[56:57], v[166:167]
	s_nop 1
	v_mfma_f32_16x16x32_bf16 v[54:57], v[152:155], v[66:69], v[54:57]
	v_mul_f32_e32 v148, v62, v62
	v_mul_f32_e32 v149, v58, v58
	v_fmac_f32_e32 v148, v63, v63
	v_fmac_f32_e32 v149, v59, v59
	v_fmac_f32_e32 v148, v64, v64
	v_fmac_f32_e32 v149, v60, v60
	v_fmac_f32_e32 v148, v65, v65
	v_fmac_f32_e32 v149, v61, v61
	v_lshl_add_u32 v156, v77, 5, s29
	s_nop 0
	v_permlane16_swap_b32_e32 v148, v149
	v_add_f32_e32 v148, v148, v149
	v_mov_b32_e32 v149, v148
	s_nop 1
	v_permlane32_swap_b32_e32 v148, v149
	v_add_f32_e32 v148, v148, v149
	s_mov_b64 s[22:23], exec
	s_mov_b32 exec_hi, 0
	ds_write_b32 v156, v148 offset:57344
	s_mov_b64 exec, s[22:23]
	s_waitcnt lgkmcnt(0)
	s_barrier
	s_andn2_b64 vcc, exec, s[20:21]
	s_cbranch_vccnz .LBB0_1330
	v_add3_u32 v68, s28, v96, v120
	ds_read_b64_tr_b16 v[66:67], v68 offset:17408
	ds_read_b64_tr_b16 v[68:69], v68 offset:18688
	v_add_u32_e32 v138, s28, v236
	v_add3_u32 v139, s28, v109, v222
	ds_read_b64 v[180:181], v138 offset:17408
	ds_read_b64 v[182:183], v138 offset:22528
	ds_read_b64 v[184:185], v139
	ds_read_b64 v[186:187], v139 offset:4352
	s_waitcnt lgkmcnt(4)
	v_mfma_f32_16x16x32_bf16 v[70:73], v[66:69], v[4:7], 0
	v_mfma_f32_16x16x32_bf16 v[66:69], v[66:69], v[0:3], 0
	s_mov_b32 s23, 0x42e60000
	s_waitcnt lgkmcnt(0)
	v_lshlrev_b32_e32 v188, 16, v180
	v_and_b32_e32 v189, 0xffff0000, v180
	v_lshlrev_b32_e32 v190, 16, v181
	v_and_b32_e32 v191, 0xffff0000, v181
	v_lshlrev_b32_e32 v192, 16, v182
	v_and_b32_e32 v193, 0xffff0000, v182
	v_lshlrev_b32_e32 v194, 16, v183
	v_and_b32_e32 v195, 0xffff0000, v183
	v_lshlrev_b32_e32 v196, 16, v184
	v_and_b32_e32 v197, 0xffff0000, v184
	v_lshlrev_b32_e32 v198, 16, v185
	v_and_b32_e32 v199, 0xffff0000, v185
	v_lshlrev_b32_e32 v200, 16, v186
	v_and_b32_e32 v201, 0xffff0000, v186
	v_lshlrev_b32_e32 v202, 16, v187
	v_and_b32_e32 v203, 0xffff0000, v187
	v_exp_f32_e32 v188, v188
	v_exp_f32_e32 v189, v189
	v_exp_f32_e32 v190, v190
	v_exp_f32_e32 v191, v191
	v_exp_f32_e32 v192, v192
	v_exp_f32_e32 v193, v193
	v_exp_f32_e32 v194, v194
	v_exp_f32_e32 v195, v195
	v_sub_f32_e32 v188, 1.0, v188
	v_sub_f32_e32 v189, 1.0, v189
	v_sub_f32_e32 v190, 1.0, v190
	v_sub_f32_e32 v191, 1.0, v191
	v_sub_f32_e32 v192, 1.0, v192
	v_sub_f32_e32 v193, 1.0, v193
	v_sub_f32_e32 v194, 1.0, v194
	v_sub_f32_e32 v195, 1.0, v195
	v_exp_f32_e32 v204, v70
	v_exp_f32_e32 v205, v71
	v_exp_f32_e32 v206, v72
	v_exp_f32_e32 v207, v73
	v_exp_f32_e32 v208, v66
	v_exp_f32_e32 v209, v67
	v_exp_f32_e32 v210, v68
	v_exp_f32_e32 v211, v69
	v_sub_f32_dpp v126, v66, v70 row_newbcast:15 row_mask:0xf bank_mask:0xf
	v_sub_f32_dpp v127, v67, v71 row_newbcast:15 row_mask:0xf bank_mask:0xf
	v_sub_f32_dpp v128, v68, v72 row_newbcast:15 row_mask:0xf bank_mask:0xf
	v_sub_f32_dpp v129, v69, v73 row_newbcast:15 row_mask:0xf bank_mask:0xf
	v_sub_f32_dpp v130, v66, v66 row_newbcast:15 row_mask:0xf bank_mask:0xf
	v_sub_f32_dpp v131, v67, v67 row_newbcast:15 row_mask:0xf bank_mask:0xf
	v_sub_f32_dpp v132, v68, v68 row_newbcast:15 row_mask:0xf bank_mask:0xf
	v_sub_f32_dpp v133, v69, v69 row_newbcast:15 row_mask:0xf bank_mask:0xf
	v_mul_f32_e32 v196, v196, v204
	v_mul_f32_e32 v197, v197, v205
	v_mul_f32_e32 v198, v198, v206
	v_mul_f32_e32 v199, v199, v207
	v_mul_f32_e32 v200, v200, v208
	v_mul_f32_e32 v201, v201, v209
	v_mul_f32_e32 v202, v202, v210
	v_mul_f32_e32 v203, v203, v211
	v_min_f32_e64 v204, -v70, s23
	v_min_f32_e64 v205, -v71, s23
	v_min_f32_e64 v206, -v72, s23
	v_min_f32_e64 v207, -v73, s23
	v_min_f32_e64 v208, -v66, s23
	v_min_f32_e64 v209, -v67, s23
	v_min_f32_e64 v210, -v68, s23
	v_min_f32_e64 v211, -v69, s23
	v_exp_f32_e32 v126, v126
	v_exp_f32_e32 v127, v127
	v_exp_f32_e32 v128, v128
	v_exp_f32_e32 v129, v129
	v_exp_f32_e32 v130, v130
	v_exp_f32_e32 v131, v131
	v_exp_f32_e32 v132, v132
	v_exp_f32_e32 v133, v133
	v_exp_f32_e32 v204, v204
	v_exp_f32_e32 v205, v205
	v_exp_f32_e32 v206, v206
	v_exp_f32_e32 v207, v207
	v_exp_f32_e32 v208, v208
	v_exp_f32_e32 v209, v209
	v_exp_f32_e32 v210, v210
	v_exp_f32_e32 v211, v211
	v_exp_f32_e32 v212, v66
	v_exp_f32_e32 v213, v67
	v_exp_f32_e32 v214, v68
	v_exp_f32_e32 v215, v69
	v_mul_f32_e32 v126, v126, v188
	v_mul_f32_e32 v127, v127, v189
	v_mul_f32_e32 v128, v128, v190
	v_mul_f32_e32 v129, v129, v191
	v_mul_f32_e32 v130, v130, v192
	v_mul_f32_e32 v131, v131, v193
	v_mul_f32_e32 v132, v132, v194
	v_mul_f32_e32 v133, v133, v195
	v_mul_f32_e32 v204, v204, v188
	v_mul_f32_e32 v205, v205, v189
	v_mul_f32_e32 v206, v206, v190
	v_mul_f32_e32 v207, v207, v191
	v_mul_f32_e32 v208, v208, v192
	v_mul_f32_e32 v209, v209, v193
	v_mul_f32_e32 v210, v210, v194
	v_mul_f32_e32 v211, v211, v195
	v_lshl_add_u32 v216, v222, 1, s28
	v_cvt_pk_bf16_f32 v180, v196, v197
	v_cvt_pk_bf16_f32 v181, v198, v199
	v_cvt_pk_bf16_f32 v182, v200, v201
	v_cvt_pk_bf16_f32 v183, v202, v203
	v_cvt_pk_bf16_f32 v184, v204, v205
	v_cvt_pk_bf16_f32 v185, v206, v207
	v_cvt_pk_bf16_f32 v186, v208, v209
	v_cvt_pk_bf16_f32 v187, v210, v211
	v_cvt_pk_bf16_f32 v134, v126, v127
	v_cvt_pk_bf16_f32 v135, v128, v129
	v_cvt_pk_bf16_f32 v136, v130, v131
	v_cvt_pk_bf16_f32 v137, v132, v133
	ds_write_b64 v139, v[180:181]
	ds_write_b64 v139, v[182:183] offset:4352
	ds_write_b64 v139, v[184:185] offset:8704
	ds_write_b64 v139, v[186:187] offset:13056
	ds_write_b64 v138, v[134:135] offset:27648
	ds_write_b64 v138, v[136:137] offset:32768
	s_and_saveexec_b64 s[20:21], s[2:3]
	ds_write_b128 v216, v[212:215] offset:56832
	s_branch .LBB0_1329
